# strategy 7 continued: sign flips before the bf16 conversions folded into v_cvt_pk_bf16_f32 source negate modifiers (94 sites in the phase-3 triangular solve)
# speedup vs baseline: 1.0028x; 1.0028x over previous
.LBB0_355:
	s_and_b64 vcc, exec, s[18:19]
	s_cbranch_vccz .LBB0_421
	v_add_u32_e32 v2, v171, v187
	ds_read_b128 v[4:7], v2 offset:272
	v_mov_b32_e32 v2, v188
	s_waitcnt lgkmcnt(0)
	v_fma_f32 v17, -v195, v4, v196
	v_add_u32_e32 v3, 0, v2
	ds_read_b128 v[6:9], v3 offset:544
	s_nop 0
	v_add_u32_e32 v3, 0, v2
	s_waitcnt lgkmcnt(0)
	ds_read_b128 v[8:11], v3 offset:816
	v_fma_f32 v3, -v195, v6, v197
	v_fma_f32 v4, -v7, v17, 0
	v_add_f32_e32 v15, v4, v3
	s_nop 0
	v_add_u32_e32 v3, 0, v2
	ds_read_b128 v[4:7], v3 offset:1088
	s_waitcnt lgkmcnt(1)
	v_fma_f32 v3, -v195, v8, v198
	v_fma_f32 v8, -v17, v9, 0
	v_fma_f32 v9, -v10, v15, 0
	v_add_f32_e32 v3, v8, v3
	v_add_f32_e32 v13, v9, v3
	s_nop 0
	v_add_u32_e32 v3, 0, v2
	ds_read_b128 v[18:21], v3 offset:1360
	ds_read_b128 v[8:11], v3 offset:1376
	s_waitcnt lgkmcnt(2)
	v_fma_f32 v3, -v195, v4, v199
	v_fma_f32 v4, -v17, v5, 0
	v_fma_f32 v5, -v15, v6, 0
	v_fma_f32 v6, -v7, v13, 0
	v_add_f32_e32 v3, v4, v3
	v_add_f32_e32 v4, v6, v5
	s_waitcnt lgkmcnt(0)
	v_add_f32_e32 v11, v4, v3
	v_fma_f32 v9, -v17, v19, 0
	v_add_u32_e32 v3, 0, v2
	ds_read_b128 v[4:7], v3 offset:1632
	ds_read_b128 v[22:25], v3 offset:1648
	v_fma_f32 v3, -v195, v18, v200
	v_fma_f32 v10, -v15, v20, 0
	v_fma_f32 v12, -v13, v21, 0
	v_fma_f32 v3, -v8, v11, v3
	v_add_f32_e32 v3, v9, v3
	v_add_f32_e32 v8, v12, v10
	v_add_f32_e32 v9, v8, v3
	s_nop 0
	v_add_u32_e32 v3, 0, v2
	ds_read_b128 v[18:21], v3 offset:1904
	ds_read_b128 v[28:31], v3 offset:1920
	s_waitcnt lgkmcnt(3)
	v_fma_f32 v3, -v195, v4, v201
	v_fma_f32 v4, -v17, v5, 0
	v_fma_f32 v5, -v15, v6, 0
	v_fma_f32 v6, -v13, v7, 0
	s_waitcnt lgkmcnt(2)
	v_fma_f32 v3, -v11, v22, v3
	v_fma_f32 v4, -v23, v9, v4
	v_add_f32_e32 v3, v4, v3
	v_add_f32_e32 v4, v6, v5
	v_add_f32_e32 v7, v4, v3
	s_waitcnt lgkmcnt(1)
	v_fma_f32 v4, -v17, v19, 0
	v_add_u32_e32 v3, 0, v2
	ds_read_b128 v[22:25], v3 offset:2176
	ds_read_b128 v[32:35], v3 offset:2192
	v_fma_f32 v3, -v195, v18, v202
	v_fma_f32 v5, -v15, v20, 0
	v_fma_f32 v6, -v13, v21, 0
	s_waitcnt lgkmcnt(2)
	v_fma_f32 v3, -v11, v28, v3
	v_fma_f32 v4, -v9, v29, v4
	v_fma_f32 v5, -v30, v7, v5
	v_add_f32_e32 v3, v4, v3
	v_add_f32_e32 v4, v6, v5
	v_add_f32_e32 v4, v4, v3
	s_waitcnt lgkmcnt(1)
	v_fma_f32 v5, -v17, v23, 0
	v_add_u32_e32 v3, 0, v2
	ds_read_b128 v[18:21], v3 offset:2448
	ds_read_b128 v[28:31], v3 offset:2464
	ds_read_b128 v[36:39], v3 offset:2480
	v_fma_f32 v3, -v195, v22, v203
	v_fma_f32 v6, -v15, v24, 0
	v_fma_f32 v8, -v13, v25, 0
	s_waitcnt lgkmcnt(3)
	v_fma_f32 v3, -v11, v32, v3
	v_fma_f32 v5, -v9, v33, v5
	v_fma_f32 v6, -v7, v34, v6
	v_fma_f32 v8, -v35, v4, v8
	v_add_f32_e32 v3, v5, v3
	v_add_f32_e32 v5, v8, v6
	v_add_f32_e32 v5, v5, v3
	s_waitcnt lgkmcnt(2)
	v_fma_f32 v6, -v17, v19, 0
	v_add_u32_e32 v3, 0, v2
	ds_read_b128 v[22:25], v3 offset:2720
	ds_read_b128 v[32:35], v3 offset:2736
	s_waitcnt lgkmcnt(2)
	ds_read_b128 v[38:41], v3 offset:2752
	v_fma_f32 v3, -v195, v18, v204
	v_fma_f32 v8, -v15, v20, 0
	v_fma_f32 v10, -v13, v21, 0
	v_fma_f32 v3, -v11, v28, v3
	v_fma_f32 v6, -v9, v29, v6
	v_fma_f32 v8, -v7, v30, v8
	v_fma_f32 v10, -v4, v31, v10
	v_fma_f32 v3, -v36, v5, v3
	v_add_f32_e32 v3, v6, v3
	v_add_f32_e32 v6, v10, v8
	v_add_f32_e32 v6, v6, v3
	s_waitcnt lgkmcnt(2)
	v_fma_f32 v8, -v17, v23, 0
	v_add_u32_e32 v3, 0, v2
	ds_read_b128 v[18:21], v3 offset:2992
	ds_read_b128 v[28:31], v3 offset:3008
	s_waitcnt lgkmcnt(2)
	ds_read_b128 v[40:43], v3 offset:3024
	v_fma_f32 v3, -v195, v22, v205
	v_fma_f32 v10, -v15, v24, 0
	v_fma_f32 v12, -v13, v25, 0
	v_fma_f32 v3, -v11, v32, v3
	v_fma_f32 v8, -v9, v33, v8
	v_fma_f32 v10, -v7, v34, v10
	v_fma_f32 v12, -v4, v35, v12
	v_fma_f32 v3, -v5, v38, v3
	v_fma_f32 v8, -v39, v6, v8
	v_add_f32_e32 v3, v8, v3
	v_add_f32_e32 v8, v12, v10
	v_add_f32_e32 v8, v8, v3
	s_waitcnt lgkmcnt(2)
	v_fma_f32 v10, -v17, v19, 0
	v_add_u32_e32 v3, 0, v2
	ds_read_b128 v[22:25], v3 offset:3264
	ds_read_b128 v[32:35], v3 offset:3280
	ds_read_b128 v[36:39], v3 offset:3296
	v_fma_f32 v3, -v195, v18, v206
	v_fma_f32 v12, -v15, v20, 0
	v_fma_f32 v14, -v13, v21, 0
	s_waitcnt lgkmcnt(4)
	v_fma_f32 v3, -v11, v28, v3
	v_fma_f32 v10, -v9, v29, v10
	v_fma_f32 v12, -v7, v30, v12
	v_fma_f32 v14, -v4, v31, v14
	s_waitcnt lgkmcnt(3)
	v_fma_f32 v3, -v5, v40, v3
	v_fma_f32 v10, -v6, v41, v10
	v_fma_f32 v12, -v42, v8, v12
	v_add_f32_e32 v3, v10, v3
	v_add_f32_e32 v10, v14, v12
	v_add_f32_e32 v10, v10, v3
	s_waitcnt lgkmcnt(2)
	v_fma_f32 v12, -v17, v23, 0
	v_add_u32_e32 v3, 0, v2
	ds_read_b128 v[18:21], v3 offset:3536
	ds_read_b128 v[28:31], v3 offset:3552
	ds_read_b128 v[40:43], v3 offset:3568
	ds_read_b128 v[44:47], v3 offset:3584
	v_fma_f32 v3, -v195, v22, v207
	v_fma_f32 v14, -v15, v24, 0
	v_fma_f32 v16, -v13, v25, 0
	s_waitcnt lgkmcnt(5)
	v_fma_f32 v3, -v11, v32, v3
	v_fma_f32 v12, -v9, v33, v12
	v_fma_f32 v14, -v7, v34, v14
	v_fma_f32 v16, -v4, v35, v16
	s_waitcnt lgkmcnt(4)
	v_fma_f32 v3, -v5, v36, v3
	v_fma_f32 v12, -v6, v37, v12
	v_fma_f32 v14, -v8, v38, v14
	v_fma_f32 v16, -v39, v10, v16
	v_add_f32_e32 v3, v12, v3
	v_add_f32_e32 v12, v16, v14
	v_add_f32_e32 v12, v12, v3
	s_waitcnt lgkmcnt(3)
	v_fma_f32 v14, -v17, v19, 0
	v_add_u32_e32 v3, 0, v2
	ds_read_b128 v[22:25], v3 offset:3808
	ds_read_b128 v[32:35], v3 offset:3824
	ds_read_b128 v[36:39], v3 offset:3840
	s_waitcnt lgkmcnt(3)
	ds_read_b128 v[46:49], v3 offset:3856
	v_fma_f32 v3, -v195, v18, v208
	v_fma_f32 v16, -v15, v20, 0
	v_fma_f32 v18, -v13, v21, 0
	v_fma_f32 v3, -v11, v28, v3
	v_fma_f32 v14, -v9, v29, v14
	v_fma_f32 v16, -v7, v30, v16
	v_fma_f32 v18, -v4, v31, v18
	v_fma_f32 v3, -v5, v40, v3
	v_fma_f32 v14, -v6, v41, v14
	v_fma_f32 v16, -v8, v42, v16
	v_fma_f32 v18, -v10, v43, v18
	v_fma_f32 v3, -v44, v12, v3
	v_add_f32_e32 v3, v14, v3
	v_add_f32_e32 v14, v18, v16
	v_add_f32_e32 v14, v14, v3
	s_waitcnt lgkmcnt(3)
	v_fma_f32 v16, -v17, v23, 0
	v_add_u32_e32 v3, 0, v2
	ds_read_b128 v[18:21], v3 offset:4080
	ds_read_b128 v[28:31], v3 offset:4096
	ds_read_b128 v[40:43], v3 offset:4112
	s_waitcnt lgkmcnt(3)
	ds_read_b128 v[48:51], v3 offset:4128
	v_fma_f32 v3, -v195, v22, v209
	v_fma_f32 v22, -v15, v24, 0
	v_fma_f32 v23, -v13, v25, 0
	v_fma_f32 v3, -v11, v32, v3
	v_fma_f32 v16, -v9, v33, v16
	v_fma_f32 v22, -v7, v34, v22
	v_fma_f32 v23, -v4, v35, v23
	v_fma_f32 v3, -v5, v36, v3
	v_fma_f32 v16, -v6, v37, v16
	v_fma_f32 v22, -v8, v38, v22
	v_fma_f32 v23, -v10, v39, v23
	v_fma_f32 v3, -v12, v46, v3
	v_fma_f32 v16, -v47, v14, v16
	v_add_f32_e32 v3, v16, v3
	v_add_f32_e32 v16, v23, v22
	v_add_f32_e32 v16, v16, v3
	s_nop 0
	v_add_u32_e32 v3, 0, v2
	ds_read_b128 v[22:25], v3 offset:4352
	ds_read_b128 v[32:35], v3 offset:4368
	ds_read_b128 v[36:39], v3 offset:4384
	ds_read_b128 v[44:47], v3 offset:4400
	s_waitcnt lgkmcnt(7)
	v_fma_f32 v3, -v195, v18, v210
	v_fma_f32 v18, -v17, v19, 0
	v_fma_f32 v19, -v15, v20, 0
	v_fma_f32 v20, -v13, v21, 0
	s_waitcnt lgkmcnt(6)
	v_fma_f32 v3, -v11, v28, v3
	v_fma_f32 v18, -v9, v29, v18
	v_fma_f32 v19, -v7, v30, v19
	v_fma_f32 v20, -v4, v31, v20
	s_waitcnt lgkmcnt(5)
	v_fma_f32 v3, -v5, v40, v3
	v_fma_f32 v18, -v6, v41, v18
	v_fma_f32 v19, -v8, v42, v19
	v_fma_f32 v20, -v10, v43, v20
	s_waitcnt lgkmcnt(4)
	v_fma_f32 v3, -v12, v48, v3
	v_fma_f32 v18, -v14, v49, v18
	v_fma_f32 v19, -v50, v16, v19
	v_add_f32_e32 v3, v18, v3
	v_add_f32_e32 v18, v20, v19
	v_add_f32_e32 v18, v18, v3
	s_waitcnt lgkmcnt(3)
	v_fma_f32 v19, -v17, v23, 0
	v_add_u32_e32 v3, 0, v2
	ds_read_b128 v[28:31], v3 offset:4624
	ds_read_b128 v[40:43], v3 offset:4640
	ds_read_b128 v[48:51], v3 offset:4656
	ds_read_b128 v[52:55], v3 offset:4672
	ds_read_b128 v[56:59], v3 offset:4688
	v_fma_f32 v3, -v195, v22, v211
	v_fma_f32 v20, -v15, v24, 0
	v_fma_f32 v21, -v13, v25, 0
	s_waitcnt lgkmcnt(7)
	v_fma_f32 v3, -v11, v32, v3
	v_fma_f32 v19, -v9, v33, v19
	v_fma_f32 v20, -v7, v34, v20
	v_fma_f32 v21, -v4, v35, v21
	s_waitcnt lgkmcnt(6)
	v_fma_f32 v3, -v5, v36, v3
	v_fma_f32 v19, -v6, v37, v19
	v_fma_f32 v20, -v8, v38, v20
	v_fma_f32 v21, -v10, v39, v21
	s_waitcnt lgkmcnt(5)
	v_fma_f32 v3, -v12, v44, v3
	v_fma_f32 v19, -v14, v45, v19
	v_fma_f32 v20, -v16, v46, v20
	v_fma_f32 v21, -v47, v18, v21
	v_add_f32_e32 v3, v19, v3
	v_add_f32_e32 v19, v21, v20
	v_add_f32_e32 v19, v19, v3
	s_waitcnt lgkmcnt(4)
	v_fma_f32 v20, -v17, v29, 0
	v_add_u32_e32 v3, 0, v2
	ds_read_b128 v[22:25], v3 offset:4896
	ds_read_b128 v[32:35], v3 offset:4912
	ds_read_b128 v[36:39], v3 offset:4928
	ds_read_b128 v[44:47], v3 offset:4944
	s_waitcnt lgkmcnt(4)
	ds_read_b128 v[58:61], v3 offset:4960
	v_fma_f32 v3, -v195, v28, v212
	v_fma_f32 v21, -v15, v30, 0
	v_fma_f32 v27, -v13, v31, 0
	v_fma_f32 v3, -v11, v40, v3
	v_fma_f32 v20, -v9, v41, v20
	v_fma_f32 v21, -v7, v42, v21
	v_fma_f32 v27, -v4, v43, v27
	v_fma_f32 v3, -v5, v48, v3
	v_fma_f32 v20, -v6, v49, v20
	v_fma_f32 v21, -v8, v50, v21
	v_fma_f32 v27, -v10, v51, v27
	v_fma_f32 v3, -v12, v52, v3
	v_fma_f32 v20, -v14, v53, v20
	v_fma_f32 v21, -v16, v54, v21
	v_fma_f32 v27, -v18, v55, v27
	v_fma_f32 v3, -v56, v19, v3
	v_add_f32_e32 v3, v20, v3
	v_add_f32_e32 v20, v27, v21
	v_add_f32_e32 v20, v20, v3
	s_waitcnt lgkmcnt(4)
	v_fma_f32 v21, -v17, v23, 0
	v_add_u32_e32 v3, 0, v2
	ds_read_b128 v[28:31], v3 offset:5168
	ds_read_b128 v[40:43], v3 offset:5184
	ds_read_b128 v[48:51], v3 offset:5200
	ds_read_b128 v[52:55], v3 offset:5216
	s_waitcnt lgkmcnt(4)
	ds_read_b128 v[60:63], v3 offset:5232
	v_fma_f32 v3, -v195, v22, v213
	v_fma_f32 v22, -v15, v24, 0
	v_fma_f32 v23, -v13, v25, 0
	v_fma_f32 v3, -v11, v32, v3
	v_fma_f32 v21, -v9, v33, v21
	v_fma_f32 v22, -v7, v34, v22
	v_fma_f32 v23, -v4, v35, v23
	v_fma_f32 v3, -v5, v36, v3
	v_fma_f32 v21, -v6, v37, v21
	v_fma_f32 v22, -v8, v38, v22
	v_fma_f32 v23, -v10, v39, v23
	v_fma_f32 v3, -v12, v44, v3
	v_fma_f32 v21, -v14, v45, v21
	v_fma_f32 v22, -v16, v46, v22
	v_fma_f32 v23, -v18, v47, v23
	v_fma_f32 v3, -v19, v58, v3
	v_fma_f32 v21, -v59, v20, v21
	v_add_f32_e32 v3, v21, v3
	v_add_f32_e32 v21, v23, v22
	v_add_f32_e32 v21, v21, v3
	s_waitcnt lgkmcnt(4)
	v_fma_f32 v22, -v17, v29, 0
	v_add_u32_e32 v3, 0, v2
	ds_read_b128 v[32:35], v3 offset:5440
	ds_read_b128 v[36:39], v3 offset:5456
	ds_read_b128 v[44:47], v3 offset:5472
	ds_read_b128 v[56:59], v3 offset:5488
	ds_read_b128 v[64:67], v3 offset:5504
	v_fma_f32 v3, -v195, v28, v214
	v_fma_f32 v23, -v15, v30, 0
	v_fma_f32 v24, -v13, v31, 0
	s_waitcnt lgkmcnt(8)
	v_fma_f32 v3, -v11, v40, v3
	v_fma_f32 v22, -v9, v41, v22
	v_fma_f32 v23, -v7, v42, v23
	v_fma_f32 v24, -v4, v43, v24
	s_waitcnt lgkmcnt(7)
	v_fma_f32 v3, -v5, v48, v3
	v_fma_f32 v22, -v6, v49, v22
	v_fma_f32 v23, -v8, v50, v23
	v_fma_f32 v24, -v10, v51, v24
	s_waitcnt lgkmcnt(6)
	v_fma_f32 v3, -v12, v52, v3
	v_fma_f32 v22, -v14, v53, v22
	v_fma_f32 v23, -v16, v54, v23
	v_fma_f32 v24, -v18, v55, v24
	s_waitcnt lgkmcnt(5)
	v_fma_f32 v3, -v19, v60, v3
	v_fma_f32 v22, -v20, v61, v22
	v_fma_f32 v23, -v62, v21, v23
	v_add_f32_e32 v3, v22, v3
	v_add_f32_e32 v22, v24, v23
	v_add_f32_e32 v22, v22, v3
	s_waitcnt lgkmcnt(4)
	v_fma_f32 v23, -v17, v33, 0
	v_add_u32_e32 v3, 0, v2
	ds_read_b128 v[28:31], v3 offset:5712
	ds_read_b128 v[40:43], v3 offset:5728
	ds_read_b128 v[48:51], v3 offset:5744
	ds_read_b128 v[52:55], v3 offset:5760
	ds_read_b128 v[60:63], v3 offset:5776
	ds_read_b128 v[68:71], v3 offset:5792
	v_fma_f32 v3, -v195, v32, v215
	v_fma_f32 v24, -v15, v34, 0
	v_fma_f32 v25, -v13, v35, 0
	s_waitcnt lgkmcnt(9)
	v_fma_f32 v3, -v11, v36, v3
	v_fma_f32 v23, -v9, v37, v23
	v_fma_f32 v24, -v7, v38, v24
	v_fma_f32 v25, -v4, v39, v25
	s_waitcnt lgkmcnt(8)
	v_fma_f32 v3, -v5, v44, v3
	v_fma_f32 v23, -v6, v45, v23
	v_fma_f32 v24, -v8, v46, v24
	v_fma_f32 v25, -v10, v47, v25
	s_waitcnt lgkmcnt(7)
	v_fma_f32 v3, -v12, v56, v3
	v_fma_f32 v23, -v14, v57, v23
	v_fma_f32 v24, -v16, v58, v24
	v_fma_f32 v25, -v18, v59, v25
	s_waitcnt lgkmcnt(6)
	v_fma_f32 v3, -v19, v64, v3
	v_fma_f32 v23, -v20, v65, v23
	v_fma_f32 v24, -v21, v66, v24
	v_fma_f32 v25, -v67, v22, v25
	v_add_f32_e32 v3, v23, v3
	v_add_f32_e32 v23, v25, v24
	v_add_f32_e32 v23, v23, v3
	s_waitcnt lgkmcnt(5)
	v_fma_f32 v24, -v17, v29, 0
	v_add_u32_e32 v3, 0, v2
	ds_read_b128 v[32:35], v3 offset:5984
	ds_read_b128 v[36:39], v3 offset:6000
	ds_read_b128 v[44:47], v3 offset:6016
	ds_read_b128 v[56:59], v3 offset:6032
	ds_read_b128 v[64:67], v3 offset:6048
	s_waitcnt lgkmcnt(5)
	ds_read_b128 v[70:73], v3 offset:6064
	v_fma_f32 v3, -v195, v28, v216
	v_fma_f32 v25, -v15, v30, 0
	v_fma_f32 v27, -v13, v31, 0
	v_fma_f32 v3, -v11, v40, v3
	v_fma_f32 v24, -v9, v41, v24
	v_fma_f32 v25, -v7, v42, v25
	v_fma_f32 v27, -v4, v43, v27
	v_fma_f32 v3, -v5, v48, v3
	v_fma_f32 v24, -v6, v49, v24
	v_fma_f32 v25, -v8, v50, v25
	v_fma_f32 v27, -v10, v51, v27
	v_fma_f32 v3, -v12, v52, v3
	v_fma_f32 v24, -v14, v53, v24
	v_fma_f32 v25, -v16, v54, v25
	v_fma_f32 v27, -v18, v55, v27
	v_fma_f32 v3, -v19, v60, v3
	v_fma_f32 v24, -v20, v61, v24
	v_fma_f32 v25, -v21, v62, v25
	v_fma_f32 v27, -v22, v63, v27
	v_fma_f32 v3, -v68, v23, v3
	v_add_f32_e32 v3, v24, v3
	v_add_f32_e32 v24, v27, v25
	v_add_f32_e32 v24, v24, v3
	s_waitcnt lgkmcnt(5)
	v_fma_f32 v25, -v17, v33, 0
	v_add_u32_e32 v3, 0, v2
	ds_read_b128 v[28:31], v3 offset:6256
	ds_read_b128 v[40:43], v3 offset:6272
	ds_read_b128 v[48:51], v3 offset:6288
	ds_read_b128 v[52:55], v3 offset:6304
	ds_read_b128 v[60:63], v3 offset:6320
	s_waitcnt lgkmcnt(5)
	ds_read_b128 v[72:75], v3 offset:6336
	v_fma_f32 v3, -v195, v32, v217
	v_fma_f32 v27, -v15, v34, 0
	v_fma_f32 v32, -v13, v35, 0
	v_fma_f32 v3, -v11, v36, v3
	v_fma_f32 v25, -v9, v37, v25
	v_fma_f32 v27, -v7, v38, v27
	v_fma_f32 v32, -v4, v39, v32
	v_fma_f32 v3, -v5, v44, v3
	v_fma_f32 v25, -v6, v45, v25
	v_fma_f32 v27, -v8, v46, v27
	v_fma_f32 v32, -v10, v47, v32
	v_fma_f32 v3, -v12, v56, v3
	v_fma_f32 v25, -v14, v57, v25
	v_fma_f32 v27, -v16, v58, v27
	v_fma_f32 v32, -v18, v59, v32
	v_fma_f32 v3, -v19, v64, v3
	v_fma_f32 v25, -v20, v65, v25
	v_fma_f32 v27, -v21, v66, v27
	v_fma_f32 v32, -v22, v67, v32
	v_fma_f32 v3, -v23, v70, v3
	v_fma_f32 v25, -v71, v24, v25
	v_add_f32_e32 v3, v25, v3
	v_add_f32_e32 v25, v32, v27
	v_add_f32_e32 v25, v25, v3
	s_waitcnt lgkmcnt(5)
	v_fma_f32 v27, -v17, v29, 0
	v_add_u32_e32 v3, 0, v2
	ds_read_b128 v[32:35], v3 offset:6528
	ds_read_b128 v[36:39], v3 offset:6544
	ds_read_b128 v[44:47], v3 offset:6560
	ds_read_b128 v[56:59], v3 offset:6576
	ds_read_b128 v[64:67], v3 offset:6592
	ds_read_b128 v[68:71], v3 offset:6608
	v_fma_f32 v3, -v195, v28, v218
	v_fma_f32 v28, -v15, v30, 0
	v_fma_f32 v29, -v13, v31, 0
	s_waitcnt lgkmcnt(10)
	v_fma_f32 v3, -v11, v40, v3
	v_fma_f32 v27, -v9, v41, v27
	v_fma_f32 v28, -v7, v42, v28
	v_fma_f32 v29, -v4, v43, v29
	s_waitcnt lgkmcnt(9)
	v_fma_f32 v3, -v5, v48, v3
	v_fma_f32 v27, -v6, v49, v27
	v_fma_f32 v28, -v8, v50, v28
	v_fma_f32 v29, -v10, v51, v29
	s_waitcnt lgkmcnt(8)
	v_fma_f32 v3, -v12, v52, v3
	v_fma_f32 v27, -v14, v53, v27
	v_fma_f32 v28, -v16, v54, v28
	v_fma_f32 v29, -v18, v55, v29
	s_waitcnt lgkmcnt(7)
	v_fma_f32 v3, -v19, v60, v3
	v_fma_f32 v27, -v20, v61, v27
	v_fma_f32 v28, -v21, v62, v28
	v_fma_f32 v29, -v22, v63, v29
	s_waitcnt lgkmcnt(6)
	v_fma_f32 v3, -v23, v72, v3
	v_fma_f32 v27, -v24, v73, v27
	v_fma_f32 v28, -v74, v25, v28
	v_add_f32_e32 v3, v27, v3
	v_add_f32_e32 v27, v29, v28
	v_add_f32_e32 v27, v27, v3
	s_waitcnt lgkmcnt(5)
	v_fma_f32 v28, -v17, v33, 0
	v_add_u32_e32 v3, 0, v2
	ds_read_b128 v[40:43], v3 offset:6800
	ds_read_b128 v[48:51], v3 offset:6816
	ds_read_b128 v[52:55], v3 offset:6832
	ds_read_b128 v[60:63], v3 offset:6848
	ds_read_b128 v[72:75], v3 offset:6864
	ds_read_b128 v[76:79], v3 offset:6880
	ds_read_b128 v[140:143], v3 offset:6896
	v_fma_f32 v3, -v195, v32, v219
	v_fma_f32 v29, -v15, v34, 0
	v_fma_f32 v30, -v13, v35, 0
	s_waitcnt lgkmcnt(11)
	v_fma_f32 v3, -v11, v36, v3
	v_fma_f32 v28, -v9, v37, v28
	v_fma_f32 v29, -v7, v38, v29
	v_fma_f32 v30, -v4, v39, v30
	s_waitcnt lgkmcnt(10)
	v_fma_f32 v3, -v5, v44, v3
	v_fma_f32 v28, -v6, v45, v28
	v_fma_f32 v29, -v8, v46, v29
	v_fma_f32 v30, -v10, v47, v30
	s_waitcnt lgkmcnt(9)
	v_fma_f32 v3, -v12, v56, v3
	v_fma_f32 v28, -v14, v57, v28
	v_fma_f32 v29, -v16, v58, v29
	v_fma_f32 v30, -v18, v59, v30
	s_waitcnt lgkmcnt(8)
	v_fma_f32 v3, -v19, v64, v3
	v_fma_f32 v28, -v20, v65, v28
	v_fma_f32 v29, -v21, v66, v29
	v_fma_f32 v30, -v22, v67, v30
	s_waitcnt lgkmcnt(7)
	v_fma_f32 v3, -v23, v68, v3
	v_fma_f32 v28, -v24, v69, v28
	v_fma_f32 v29, -v25, v70, v29
	v_fma_f32 v30, -v71, v27, v30
	v_add_f32_e32 v3, v28, v3
	v_add_f32_e32 v28, v30, v29
	v_add_f32_e32 v28, v28, v3
	s_waitcnt lgkmcnt(6)
	v_fma_f32 v29, -v17, v41, 0
	v_add_u32_e32 v3, 0, v2
	ds_read_b128 v[30:33], v3 offset:7072
	ds_read_b128 v[34:37], v3 offset:7088
	ds_read_b128 v[44:47], v3 offset:7104
	ds_read_b128 v[56:59], v3 offset:7120
	ds_read_b128 v[64:67], v3 offset:7136
	ds_read_b128 v[68:71], v3 offset:7152
	s_waitcnt lgkmcnt(6)
	ds_read_b128 v[142:145], v3 offset:7168
	v_fma_f32 v3, -v195, v40, v220
	v_fma_f32 v38, -v15, v42, 0
	v_fma_f32 v39, -v13, v43, 0
	v_fma_f32 v3, -v11, v48, v3
	v_fma_f32 v29, -v9, v49, v29
	v_fma_f32 v38, -v7, v50, v38
	v_fma_f32 v39, -v4, v51, v39
	v_fma_f32 v3, -v5, v52, v3
	v_fma_f32 v29, -v6, v53, v29
	v_fma_f32 v38, -v8, v54, v38
	v_fma_f32 v39, -v10, v55, v39
	v_fma_f32 v3, -v12, v60, v3
	v_fma_f32 v29, -v14, v61, v29
	v_fma_f32 v38, -v16, v62, v38
	v_fma_f32 v39, -v18, v63, v39
	v_fma_f32 v3, -v19, v72, v3
	v_fma_f32 v29, -v20, v73, v29
	v_fma_f32 v38, -v21, v74, v38
	v_fma_f32 v39, -v22, v75, v39
	v_fma_f32 v3, -v23, v76, v3
	v_fma_f32 v29, -v24, v77, v29
	v_fma_f32 v38, -v25, v78, v38
	v_fma_f32 v39, -v27, v79, v39
	v_fma_f32 v3, -v140, v28, v3
	v_add_f32_e32 v3, v29, v3
	v_add_f32_e32 v29, v39, v38
	v_add_f32_e32 v29, v29, v3
	s_nop 0
	v_add_u32_e32 v3, 0, v2
	ds_read_b128 v[38:41], v3 offset:7344
	ds_read_b128 v[48:51], v3 offset:7360
	ds_read_b128 v[52:55], v3 offset:7376
	ds_read_b128 v[60:63], v3 offset:7392
	ds_read_b128 v[72:75], v3 offset:7408
	ds_read_b128 v[76:79], v3 offset:7424
	s_waitcnt lgkmcnt(6)
	ds_read_b128 v[144:147], v3 offset:7440
	v_fma_f32 v3, -v195, v30, v221
	v_fma_f32 v30, -v17, v31, 0
	v_fma_f32 v31, -v15, v32, 0
	v_fma_f32 v32, -v13, v33, 0
	v_fma_f32 v3, -v11, v34, v3
	v_fma_f32 v30, -v9, v35, v30
	v_fma_f32 v31, -v7, v36, v31
	v_fma_f32 v32, -v4, v37, v32
	v_fma_f32 v3, -v5, v44, v3
	v_fma_f32 v30, -v6, v45, v30
	v_fma_f32 v31, -v8, v46, v31
	v_fma_f32 v32, -v10, v47, v32
	v_fma_f32 v3, -v12, v56, v3
	v_fma_f32 v30, -v14, v57, v30
	v_fma_f32 v31, -v16, v58, v31
	v_fma_f32 v32, -v18, v59, v32
	v_fma_f32 v3, -v19, v64, v3
	v_fma_f32 v30, -v20, v65, v30
	v_fma_f32 v31, -v21, v66, v31
	v_fma_f32 v32, -v22, v67, v32
	v_fma_f32 v3, -v23, v68, v3
	v_fma_f32 v30, -v24, v69, v30
	v_fma_f32 v31, -v25, v70, v31
	v_fma_f32 v32, -v27, v71, v32
	v_fma_f32 v3, -v28, v142, v3
	v_fma_f32 v30, -v143, v29, v30
	v_add_f32_e32 v3, v30, v3
	v_add_f32_e32 v30, v32, v31
	v_add_f32_e32 v30, v30, v3
	s_waitcnt lgkmcnt(6)
	v_fma_f32 v31, -v17, v39, 0
	v_add_u32_e32 v3, 0, v2
	ds_read_b128 v[32:35], v3 offset:7616
	ds_read_b128 v[42:45], v3 offset:7632
	ds_read_b128 v[56:59], v3 offset:7648
	ds_read_b128 v[64:67], v3 offset:7664
	ds_read_b128 v[68:71], v3 offset:7680
	ds_read_b128 v[140:143], v3 offset:7696
	ds_read_b128 v[148:151], v3 offset:7712
	v_fma_f32 v3, -v195, v38, v222
	v_fma_f32 v36, -v15, v40, 0
	v_fma_f32 v37, -v13, v41, 0
	s_waitcnt lgkmcnt(12)
	v_fma_f32 v3, -v11, v48, v3
	v_fma_f32 v31, -v9, v49, v31
	v_fma_f32 v36, -v7, v50, v36
	v_fma_f32 v37, -v4, v51, v37
	s_waitcnt lgkmcnt(11)
	v_fma_f32 v3, -v5, v52, v3
	v_fma_f32 v31, -v6, v53, v31
	v_fma_f32 v36, -v8, v54, v36
	v_fma_f32 v37, -v10, v55, v37
	s_waitcnt lgkmcnt(10)
	v_fma_f32 v3, -v12, v60, v3
	v_fma_f32 v31, -v14, v61, v31
	v_fma_f32 v36, -v16, v62, v36
	v_fma_f32 v37, -v18, v63, v37
	s_waitcnt lgkmcnt(9)
	v_fma_f32 v3, -v19, v72, v3
	v_fma_f32 v31, -v20, v73, v31
	v_fma_f32 v36, -v21, v74, v36
	v_fma_f32 v37, -v22, v75, v37
	s_waitcnt lgkmcnt(8)
	v_fma_f32 v3, -v23, v76, v3
	v_fma_f32 v31, -v24, v77, v31
	v_fma_f32 v36, -v25, v78, v36
	v_fma_f32 v37, -v27, v79, v37
	s_waitcnt lgkmcnt(7)
	v_fma_f32 v3, -v28, v144, v3
	v_fma_f32 v31, -v29, v145, v31
	v_fma_f32 v36, -v146, v30, v36
	v_add_f32_e32 v3, v31, v3
	v_add_f32_e32 v31, v37, v36
	v_add_f32_e32 v31, v31, v3
	s_nop 0
	v_add_u32_e32 v3, 0, v2
	ds_read_b128 v[36:39], v3 offset:7888
	ds_read_b128 v[46:49], v3 offset:7904
	ds_read_b128 v[50:53], v3 offset:7920
	ds_read_b128 v[60:63], v3 offset:7936
	ds_read_b128 v[72:75], v3 offset:7952
	ds_read_b128 v[76:79], v3 offset:7968
	ds_read_b128 v[144:147], v3 offset:7984
	ds_read_b128 v[152:155], v3 offset:8000
	s_waitcnt lgkmcnt(14)
	v_fma_f32 v3, -v195, v32, v223
	v_fma_f32 v32, -v17, v33, 0
	v_fma_f32 v33, -v15, v34, 0
	v_fma_f32 v34, -v13, v35, 0
	s_waitcnt lgkmcnt(13)
	v_fma_f32 v3, -v11, v42, v3
	v_fma_f32 v32, -v9, v43, v32
	v_fma_f32 v33, -v7, v44, v33
	v_fma_f32 v34, -v4, v45, v34
	s_waitcnt lgkmcnt(12)
	v_fma_f32 v3, -v5, v56, v3
	v_fma_f32 v32, -v6, v57, v32
	v_fma_f32 v33, -v8, v58, v33
	v_fma_f32 v34, -v10, v59, v34
	s_waitcnt lgkmcnt(11)
	v_fma_f32 v3, -v12, v64, v3
	v_fma_f32 v32, -v14, v65, v32
	v_fma_f32 v33, -v16, v66, v33
	v_fma_f32 v34, -v18, v67, v34
	s_waitcnt lgkmcnt(10)
	v_fma_f32 v3, -v19, v68, v3
	v_fma_f32 v32, -v20, v69, v32
	v_fma_f32 v33, -v21, v70, v33
	v_fma_f32 v34, -v22, v71, v34
	s_waitcnt lgkmcnt(9)
	v_fma_f32 v3, -v23, v140, v3
	v_fma_f32 v32, -v24, v141, v32
	v_fma_f32 v33, -v25, v142, v33
	v_fma_f32 v34, -v27, v143, v34
	s_waitcnt lgkmcnt(8)
	v_fma_f32 v3, -v28, v148, v3
	v_fma_f32 v32, -v29, v149, v32
	v_fma_f32 v33, -v30, v150, v33
	v_fma_f32 v34, -v151, v31, v34
	v_add_f32_e32 v3, v32, v3
	v_add_f32_e32 v32, v34, v33
	v_add_f32_e32 v32, v32, v3
	s_waitcnt lgkmcnt(7)
	v_fma_f32 v33, -v17, v37, 0
	v_add_u32_e32 v3, 0, v2
	ds_read_b128 v[40:43], v3 offset:8160
	ds_read_b128 v[54:57], v3 offset:8176
	ds_read_b128 v[64:67], v3 offset:8192
	ds_read_b128 v[68:71], v3 offset:8208
	ds_read_b128 v[140:143], v3 offset:8224
	ds_read_b128 v[148:151], v3 offset:8240
	s_waitcnt lgkmcnt(6)
	ds_read_b128 v[154:157], v3 offset:8256
	ds_read_b128 v[158:161], v3 offset:8272
	v_fma_f32 v3, -v195, v36, v224
	v_fma_f32 v34, -v15, v38, 0
	v_fma_f32 v35, -v13, v39, 0
	v_fma_f32 v3, -v11, v46, v3
	v_fma_f32 v33, -v9, v47, v33
	v_fma_f32 v34, -v7, v48, v34
	v_fma_f32 v35, -v4, v49, v35
	v_fma_f32 v3, -v5, v50, v3
	v_fma_f32 v33, -v6, v51, v33
	v_fma_f32 v34, -v8, v52, v34
	v_fma_f32 v35, -v10, v53, v35
	v_fma_f32 v3, -v12, v60, v3
	v_fma_f32 v33, -v14, v61, v33
	v_fma_f32 v34, -v16, v62, v34
	v_fma_f32 v35, -v18, v63, v35
	v_fma_f32 v3, -v19, v72, v3
	v_fma_f32 v33, -v20, v73, v33
	v_fma_f32 v34, -v21, v74, v34
	v_fma_f32 v35, -v22, v75, v35
	v_fma_f32 v3, -v23, v76, v3
	v_fma_f32 v33, -v24, v77, v33
	v_fma_f32 v34, -v25, v78, v34
	v_fma_f32 v35, -v27, v79, v35
	v_fma_f32 v3, -v28, v144, v3
	v_fma_f32 v33, -v29, v145, v33
	v_fma_f32 v34, -v30, v146, v34
	v_fma_f32 v35, -v31, v147, v35
	v_fma_f32 v3, -v152, v32, v3
	v_add_f32_e32 v3, v33, v3
	v_add_f32_e32 v33, v35, v34
	v_add_f32_e32 v33, v33, v3
	s_waitcnt lgkmcnt(7)
	v_fma_f32 v34, -v17, v41, 0
	v_add_u32_e32 v3, 0, v2
	ds_read_b128 v[36:39], v3 offset:8432
	ds_read_b128 v[44:47], v3 offset:8448
	ds_read_b128 v[48:51], v3 offset:8464
	ds_read_b128 v[58:61], v3 offset:8480
	ds_read_b128 v[72:75], v3 offset:8496
	ds_read_b128 v[76:79], v3 offset:8512
	ds_read_b128 v[144:147], v3 offset:8528
	s_waitcnt lgkmcnt(7)
	ds_read_b128 v[160:163], v3 offset:8544
	v_fma_f32 v3, -v195, v40, v225
	v_fma_f32 v35, -v15, v42, 0
	v_fma_f32 v40, -v13, v43, 0
	v_fma_f32 v3, -v11, v54, v3
	v_fma_f32 v34, -v9, v55, v34
	v_fma_f32 v35, -v7, v56, v35
	v_fma_f32 v40, -v4, v57, v40
	v_fma_f32 v3, -v5, v64, v3
	v_fma_f32 v34, -v6, v65, v34
	v_fma_f32 v35, -v8, v66, v35
	v_fma_f32 v40, -v10, v67, v40
	v_fma_f32 v3, -v12, v68, v3
	v_fma_f32 v34, -v14, v69, v34
	v_fma_f32 v35, -v16, v70, v35
	v_fma_f32 v40, -v18, v71, v40
	v_fma_f32 v3, -v19, v140, v3
	v_fma_f32 v34, -v20, v141, v34
	v_fma_f32 v35, -v21, v142, v35
	v_fma_f32 v40, -v22, v143, v40
	v_fma_f32 v3, -v23, v148, v3
	v_fma_f32 v34, -v24, v149, v34
	v_fma_f32 v35, -v25, v150, v35
	v_fma_f32 v40, -v27, v151, v40
	v_fma_f32 v3, -v28, v154, v3
	v_fma_f32 v34, -v29, v155, v34
	v_fma_f32 v35, -v30, v156, v35
	v_fma_f32 v40, -v31, v157, v40
	v_fma_f32 v3, -v32, v158, v3
	v_fma_f32 v34, -v159, v33, v34
	v_add_f32_e32 v3, v34, v3
	v_add_f32_e32 v34, v40, v35
	v_add_f32_e32 v34, v34, v3
	s_waitcnt lgkmcnt(7)
	v_fma_f32 v3, -v17, v37, 0
	v_fma_f32 v2, -v195, v36, v226
	v_fma_f32 v35, -v15, v38, 0
	v_fma_f32 v36, -v13, v39, 0
	s_waitcnt lgkmcnt(6)
	v_fma_f32 v2, -v11, v44, v2
	v_fma_f32 v3, -v9, v45, v3
	v_fma_f32 v35, -v7, v46, v35
	v_fma_f32 v36, -v4, v47, v36
	s_waitcnt lgkmcnt(5)
	v_fma_f32 v2, -v5, v48, v2
	v_fma_f32 v3, -v6, v49, v3
	v_fma_f32 v35, -v8, v50, v35
	v_fma_f32 v36, -v10, v51, v36
	s_waitcnt lgkmcnt(4)
	v_fma_f32 v2, -v12, v58, v2
	v_fma_f32 v3, -v14, v59, v3
	v_fma_f32 v35, -v16, v60, v35
	v_fma_f32 v36, -v18, v61, v36
	s_waitcnt lgkmcnt(3)
	v_fma_f32 v2, -v19, v72, v2
	v_fma_f32 v3, -v20, v73, v3
	v_fma_f32 v35, -v21, v74, v35
	v_fma_f32 v36, -v22, v75, v36
	s_waitcnt lgkmcnt(2)
	v_fma_f32 v2, -v23, v76, v2
	v_fma_f32 v3, -v24, v77, v3
	v_fma_f32 v35, -v25, v78, v35
	v_fma_f32 v36, -v27, v79, v36
	s_waitcnt lgkmcnt(1)
	v_fma_f32 v2, -v28, v144, v2
	v_fma_f32 v3, -v29, v145, v3
	v_fma_f32 v35, -v30, v146, v35
	v_fma_f32 v36, -v31, v147, v36
	s_waitcnt lgkmcnt(0)
	v_fma_f32 v2, -v32, v160, v2
	v_fma_f32 v3, -v33, v161, v3
	v_fma_f32 v35, -v162, v34, v35
	v_add_f32_e32 v2, v3, v2
	v_add_f32_e32 v3, v36, v35
	v_add_f32_e32 v35, v3, v2
	ds_read2st64_b32 v[2:3], v186 offset1:2
	s_waitcnt lgkmcnt(0)
	v_mul_f32_e32 v36, v2, v3
	v_mul_f32_e32 v3, v195, v2
	v_cvt_pk_bf16_f32 v3, v3, v3
	ds_write_b16 v190, v3
	v_mul_f32_e32 v3, v195, v36
	v_cvt_pk_bf16_f32 v3, v3, v3
	ds_write_b16 v190, v3 offset:64
	v_add_u32_e32 v3, v171, v189
	s_and_saveexec_b64 s[18:19], s[8:9]
	ds_write_b16 v3, v227 offset:128
	s_or_b64 exec, exec, s[18:19]
	v_mul_f32_e32 v37, v17, v2
	v_cvt_pk_bf16_f32 v37, v37, v37
	ds_write_b16 v190, v37 offset:272
	v_mul_f32_e32 v37, v17, v36
	v_bfe_u32 v38, v37, 16, 1
	v_add3_u32 v37, v37, v38, s54
	ds_write_b16_d16_hi v190, v37 offset:336
	s_and_saveexec_b64 s[18:19], s[8:9]
	v_cvt_pk_bf16_f32 v17, -v17, -v17
	ds_write_b16 v3, v17 offset:400
	s_or_b64 exec, exec, s[18:19]
	v_mul_f32_e32 v17, v15, v2
	v_cvt_pk_bf16_f32 v17, v17, v17
	ds_write_b16 v190, v17 offset:544
	v_mul_f32_e32 v17, v15, v36
	v_bfe_u32 v37, v17, 16, 1
	v_add3_u32 v17, v17, v37, s54
	ds_write_b16_d16_hi v190, v17 offset:608
	s_and_saveexec_b64 s[18:19], s[8:9]
	v_cvt_pk_bf16_f32 v15, -v15, -v15
	ds_write_b16 v3, v15 offset:672
	s_or_b64 exec, exec, s[18:19]
	v_mul_f32_e32 v15, v13, v2
	v_cvt_pk_bf16_f32 v15, v15, v15
	ds_write_b16 v190, v15 offset:816
	v_mul_f32_e32 v15, v13, v36
	v_bfe_u32 v17, v15, 16, 1
	v_add3_u32 v15, v15, v17, s54
	ds_write_b16_d16_hi v190, v15 offset:880
	s_and_saveexec_b64 s[18:19], s[8:9]
	v_cvt_pk_bf16_f32 v13, -v13, -v13
	ds_write_b16 v3, v13 offset:944
	s_or_b64 exec, exec, s[18:19]
	v_mul_f32_e32 v13, v11, v2
	v_cvt_pk_bf16_f32 v13, v13, v13
	ds_write_b16 v190, v13 offset:1088
	v_mul_f32_e32 v13, v11, v36
	v_bfe_u32 v15, v13, 16, 1
	v_add3_u32 v13, v13, v15, s54
	ds_write_b16_d16_hi v190, v13 offset:1152
	s_and_saveexec_b64 s[18:19], s[8:9]
	v_cvt_pk_bf16_f32 v11, -v11, -v11
	ds_write_b16 v3, v11 offset:1216
	s_or_b64 exec, exec, s[18:19]
	v_mul_f32_e32 v11, v9, v2
	v_cvt_pk_bf16_f32 v11, v11, v11
	ds_write_b16 v190, v11 offset:1360
	v_mul_f32_e32 v11, v9, v36
	v_bfe_u32 v13, v11, 16, 1
	v_add3_u32 v11, v11, v13, s54
	ds_write_b16_d16_hi v190, v11 offset:1424
	s_and_saveexec_b64 s[18:19], s[8:9]
	v_cvt_pk_bf16_f32 v9, -v9, -v9
	ds_write_b16 v3, v9 offset:1488
	s_or_b64 exec, exec, s[18:19]
	v_mul_f32_e32 v9, v7, v2
	v_cvt_pk_bf16_f32 v9, v9, v9
	ds_write_b16 v190, v9 offset:1632
	v_mul_f32_e32 v9, v7, v36
	v_bfe_u32 v11, v9, 16, 1
	v_add3_u32 v9, v9, v11, s54
	ds_write_b16_d16_hi v190, v9 offset:1696
	s_and_saveexec_b64 s[18:19], s[8:9]
	v_cvt_pk_bf16_f32 v7, -v7, -v7
	ds_write_b16 v3, v7 offset:1760
	s_or_b64 exec, exec, s[18:19]
	v_mul_f32_e32 v7, v4, v2
	v_cvt_pk_bf16_f32 v7, v7, v7
	ds_write_b16 v190, v7 offset:1904
	v_mul_f32_e32 v7, v4, v36
	v_bfe_u32 v9, v7, 16, 1
	v_add3_u32 v7, v7, v9, s54
	ds_write_b16_d16_hi v190, v7 offset:1968
	s_and_saveexec_b64 s[18:19], s[8:9]
	v_cvt_pk_bf16_f32 v4, -v4, -v4
	ds_write_b16 v3, v4 offset:2032
	s_or_b64 exec, exec, s[18:19]
	v_mul_f32_e32 v4, v5, v2
	v_cvt_pk_bf16_f32 v4, v4, v4
	ds_write_b16 v190, v4 offset:2176
	v_mul_f32_e32 v4, v5, v36
	v_bfe_u32 v7, v4, 16, 1
	v_add3_u32 v4, v4, v7, s54
	ds_write_b16_d16_hi v190, v4 offset:2240
	s_and_saveexec_b64 s[18:19], s[8:9]
	v_cvt_pk_bf16_f32 v4, -v5, -v5
	ds_write_b16 v3, v4 offset:2304
	s_or_b64 exec, exec, s[18:19]
	v_mul_f32_e32 v4, v6, v2
	v_cvt_pk_bf16_f32 v4, v4, v4
	ds_write_b16 v190, v4 offset:2448
	v_mul_f32_e32 v4, v6, v36
	v_cvt_pk_bf16_f32 v4, v4, v4
	ds_write_b16 v190, v4 offset:2512
	s_and_saveexec_b64 s[18:19], s[8:9]
	v_cvt_pk_bf16_f32 v4, -v6, -v6
	ds_write_b16 v3, v4 offset:2576
	s_or_b64 exec, exec, s[18:19]
	v_mul_f32_e32 v4, v8, v2
	v_cvt_pk_bf16_f32 v4, v4, v4
	ds_write_b16 v190, v4 offset:2720
	v_mul_f32_e32 v4, v8, v36
	v_cvt_pk_bf16_f32 v4, v4, v4
	ds_write_b16 v190, v4 offset:2784
	s_and_saveexec_b64 s[18:19], s[8:9]
	v_cvt_pk_bf16_f32 v4, -v8, -v8
	ds_write_b16 v3, v4 offset:2848
	s_or_b64 exec, exec, s[18:19]
	v_mul_f32_e32 v4, v10, v2
	v_cvt_pk_bf16_f32 v4, v4, v4
	ds_write_b16 v190, v4 offset:2992
	v_mul_f32_e32 v4, v10, v36
	v_cvt_pk_bf16_f32 v4, v4, v4
	ds_write_b16 v190, v4 offset:3056
	s_and_saveexec_b64 s[18:19], s[8:9]
	v_cvt_pk_bf16_f32 v4, -v10, -v10
	ds_write_b16 v3, v4 offset:3120
	s_or_b64 exec, exec, s[18:19]
	v_mul_f32_e32 v4, v12, v2
	v_cvt_pk_bf16_f32 v4, v4, v4
	ds_write_b16 v190, v4 offset:3264
	v_mul_f32_e32 v4, v12, v36
	v_cvt_pk_bf16_f32 v4, v4, v4
	ds_write_b16 v190, v4 offset:3328
	s_and_saveexec_b64 s[18:19], s[8:9]
	v_cvt_pk_bf16_f32 v4, -v12, -v12
	ds_write_b16 v3, v4 offset:3392
	s_or_b64 exec, exec, s[18:19]
	v_mul_f32_e32 v4, v14, v2
	v_cvt_pk_bf16_f32 v4, v4, v4
	ds_write_b16 v190, v4 offset:3536
	v_mul_f32_e32 v4, v14, v36
	v_cvt_pk_bf16_f32 v4, v4, v4
	ds_write_b16 v190, v4 offset:3600
	s_and_saveexec_b64 s[18:19], s[8:9]
	v_cvt_pk_bf16_f32 v4, -v14, -v14
	ds_write_b16 v3, v4 offset:3664
	s_or_b64 exec, exec, s[18:19]
	v_mul_f32_e32 v4, v16, v2
	v_cvt_pk_bf16_f32 v4, v4, v4
	ds_write_b16 v190, v4 offset:3808
	v_mul_f32_e32 v4, v16, v36
	v_cvt_pk_bf16_f32 v4, v4, v4
	ds_write_b16 v190, v4 offset:3872
	s_and_saveexec_b64 s[18:19], s[8:9]
	v_cvt_pk_bf16_f32 v4, -v16, -v16
	ds_write_b16 v3, v4 offset:3936
	s_or_b64 exec, exec, s[18:19]
	v_mul_f32_e32 v4, v18, v2
	v_cvt_pk_bf16_f32 v4, v4, v4
	ds_write_b16 v190, v4 offset:4080
	v_mul_f32_e32 v4, v18, v36
	v_cvt_pk_bf16_f32 v4, v4, v4
	ds_write_b16 v190, v4 offset:4144
	s_and_saveexec_b64 s[18:19], s[8:9]
	v_cvt_pk_bf16_f32 v4, -v18, -v18
	ds_write_b16 v3, v4 offset:4208
	s_or_b64 exec, exec, s[18:19]
	v_mul_f32_e32 v4, v19, v2
	v_cvt_pk_bf16_f32 v4, v4, v4
	ds_write_b16 v190, v4 offset:4352
	v_mul_f32_e32 v4, v19, v36
	v_cvt_pk_bf16_f32 v4, v4, v4
	ds_write_b16 v190, v4 offset:4416
	s_and_saveexec_b64 s[18:19], s[8:9]
	v_cvt_pk_bf16_f32 v4, -v19, -v19
	ds_write_b16 v3, v4 offset:4480
	s_or_b64 exec, exec, s[18:19]
	v_mul_f32_e32 v4, v20, v2
	v_cvt_pk_bf16_f32 v4, v4, v4
	ds_write_b16 v190, v4 offset:4624
	v_mul_f32_e32 v4, v20, v36
	v_cvt_pk_bf16_f32 v4, v4, v4
	ds_write_b16 v190, v4 offset:4688
	s_and_saveexec_b64 s[18:19], s[8:9]
	v_cvt_pk_bf16_f32 v4, -v20, -v20
	ds_write_b16 v3, v4 offset:4752
	s_or_b64 exec, exec, s[18:19]
	v_mul_f32_e32 v4, v21, v2
	v_cvt_pk_bf16_f32 v4, v4, v4
	ds_write_b16 v190, v4 offset:4896
	v_mul_f32_e32 v4, v21, v36
	v_cvt_pk_bf16_f32 v4, v4, v4
	ds_write_b16 v190, v4 offset:4960
	s_and_saveexec_b64 s[18:19], s[8:9]
	v_cvt_pk_bf16_f32 v4, -v21, -v21
	ds_write_b16 v3, v4 offset:5024
	s_or_b64 exec, exec, s[18:19]
	v_mul_f32_e32 v4, v22, v2
	v_cvt_pk_bf16_f32 v4, v4, v4
	ds_write_b16 v190, v4 offset:5168
	v_mul_f32_e32 v4, v22, v36
	v_cvt_pk_bf16_f32 v4, v4, v4
	ds_write_b16 v190, v4 offset:5232
	s_and_saveexec_b64 s[18:19], s[8:9]
	v_cvt_pk_bf16_f32 v4, -v22, -v22
	ds_write_b16 v3, v4 offset:5296
	s_or_b64 exec, exec, s[18:19]
	v_mul_f32_e32 v4, v23, v2
	v_cvt_pk_bf16_f32 v4, v4, v4
	ds_write_b16 v190, v4 offset:5440
	v_mul_f32_e32 v4, v23, v36
	v_cvt_pk_bf16_f32 v4, v4, v4
	ds_write_b16 v190, v4 offset:5504
	s_and_saveexec_b64 s[18:19], s[8:9]
	v_cvt_pk_bf16_f32 v4, -v23, -v23
	ds_write_b16 v3, v4 offset:5568
	s_or_b64 exec, exec, s[18:19]
	v_mul_f32_e32 v4, v24, v2
	v_cvt_pk_bf16_f32 v4, v4, v4
	ds_write_b16 v190, v4 offset:5712
	v_mul_f32_e32 v4, v24, v36
	v_cvt_pk_bf16_f32 v4, v4, v4
	ds_write_b16 v190, v4 offset:5776
	s_and_saveexec_b64 s[18:19], s[8:9]
	v_cvt_pk_bf16_f32 v4, -v24, -v24
	ds_write_b16 v3, v4 offset:5840
	s_or_b64 exec, exec, s[18:19]
	v_mul_f32_e32 v4, v25, v2
	v_cvt_pk_bf16_f32 v4, v4, v4
	ds_write_b16 v190, v4 offset:5984
	v_mul_f32_e32 v4, v25, v36
	v_cvt_pk_bf16_f32 v4, v4, v4
	ds_write_b16 v190, v4 offset:6048
	s_and_saveexec_b64 s[18:19], s[8:9]
	v_cvt_pk_bf16_f32 v4, -v25, -v25
	ds_write_b16 v3, v4 offset:6112
	s_or_b64 exec, exec, s[18:19]
	v_mul_f32_e32 v4, v27, v2
	v_cvt_pk_bf16_f32 v4, v4, v4
	ds_write_b16 v190, v4 offset:6256
	v_mul_f32_e32 v4, v27, v36
	v_cvt_pk_bf16_f32 v4, v4, v4
	ds_write_b16 v190, v4 offset:6320
	s_and_saveexec_b64 s[18:19], s[8:9]
	v_cvt_pk_bf16_f32 v4, -v27, -v27
	ds_write_b16 v3, v4 offset:6384
	s_or_b64 exec, exec, s[18:19]
	v_mul_f32_e32 v4, v28, v2
	v_cvt_pk_bf16_f32 v4, v4, v4
	ds_write_b16 v190, v4 offset:6528
	v_mul_f32_e32 v4, v28, v36
	v_cvt_pk_bf16_f32 v4, v4, v4
	ds_write_b16 v190, v4 offset:6592
	s_and_saveexec_b64 s[18:19], s[8:9]
	v_cvt_pk_bf16_f32 v4, -v28, -v28
	ds_write_b16 v3, v4 offset:6656
	s_or_b64 exec, exec, s[18:19]
	v_mul_f32_e32 v4, v29, v2
	v_cvt_pk_bf16_f32 v4, v4, v4
	ds_write_b16 v190, v4 offset:6800
	v_mul_f32_e32 v4, v29, v36
	v_cvt_pk_bf16_f32 v4, v4, v4
	ds_write_b16 v190, v4 offset:6864
	s_and_saveexec_b64 s[18:19], s[8:9]
	v_cvt_pk_bf16_f32 v4, -v29, -v29
	ds_write_b16 v3, v4 offset:6928
	s_or_b64 exec, exec, s[18:19]
	v_mul_f32_e32 v4, v30, v2
	v_cvt_pk_bf16_f32 v4, v4, v4
	ds_write_b16 v190, v4 offset:7072
	v_mul_f32_e32 v4, v30, v36
	v_cvt_pk_bf16_f32 v4, v4, v4
	ds_write_b16 v190, v4 offset:7136
	s_and_saveexec_b64 s[18:19], s[8:9]
	v_cvt_pk_bf16_f32 v4, -v30, -v30
	ds_write_b16 v3, v4 offset:7200
	s_or_b64 exec, exec, s[18:19]
	v_mul_f32_e32 v4, v31, v2
	v_cvt_pk_bf16_f32 v4, v4, v4
	ds_write_b16 v190, v4 offset:7344
	v_mul_f32_e32 v4, v31, v36
	v_cvt_pk_bf16_f32 v4, v4, v4
	ds_write_b16 v190, v4 offset:7408
	s_and_saveexec_b64 s[18:19], s[8:9]
	v_cvt_pk_bf16_f32 v4, -v31, -v31
	ds_write_b16 v3, v4 offset:7472
	s_or_b64 exec, exec, s[18:19]
	v_mul_f32_e32 v4, v32, v2
	v_cvt_pk_bf16_f32 v4, v4, v4
	ds_write_b16 v190, v4 offset:7616
	v_mul_f32_e32 v4, v32, v36
	v_cvt_pk_bf16_f32 v4, v4, v4
	ds_write_b16 v190, v4 offset:7680
	s_and_saveexec_b64 s[18:19], s[8:9]
	v_cvt_pk_bf16_f32 v4, -v32, -v32
	ds_write_b16 v3, v4 offset:7744
	s_or_b64 exec, exec, s[18:19]
	v_mul_f32_e32 v4, v33, v2
	v_cvt_pk_bf16_f32 v4, v4, v4
	ds_write_b16 v190, v4 offset:7888
	v_mul_f32_e32 v4, v33, v36
	v_cvt_pk_bf16_f32 v4, v4, v4
	ds_write_b16 v190, v4 offset:7952
	s_and_saveexec_b64 s[18:19], s[8:9]
	v_cvt_pk_bf16_f32 v4, -v33, -v33
	ds_write_b16 v3, v4 offset:8016
	s_or_b64 exec, exec, s[18:19]
	v_mul_f32_e32 v4, v34, v2
	v_cvt_pk_bf16_f32 v4, v4, v4
	ds_write_b16 v190, v4 offset:8160
	v_mul_f32_e32 v4, v34, v36
	v_cvt_pk_bf16_f32 v4, v4, v4
	ds_write_b16 v190, v4 offset:8224
	s_and_saveexec_b64 s[18:19], s[8:9]
	v_cvt_pk_bf16_f32 v4, -v34, -v34
	ds_write_b16 v3, v4 offset:8288
	s_or_b64 exec, exec, s[18:19]
	v_mul_f32_e32 v2, v35, v2
	v_cvt_pk_bf16_f32 v2, v2, v2
	ds_write_b16 v190, v2 offset:8432
	v_mul_f32_e32 v2, v35, v36
	v_cvt_pk_bf16_f32 v2, v2, v2
	ds_write_b16 v190, v2 offset:8496
	s_and_saveexec_b64 s[18:19], s[8:9]
	v_cvt_pk_bf16_f32 v2, -v35, -v35
	ds_write_b16 v3, v2 offset:8560
	s_or_b64 exec, exec, s[18:19]

.LBB0_425:
	s_and_b64 vcc, exec, s[38:39]
	s_barrier
	s_cbranch_vccz .LBB0_313
	s_movk_i32 s18, 0x440
	v_mad_u64_u32 v[66:67], s[18:19], v234, s18, v[168:169]
	v_lshlrev_b32_e32 v67, 1, v233
	v_xor_b32_e32 v2, 0x80000000, v2
	v_add3_u32 v66, v66, v67, s11
	v_cvt_pk_bf16_f32 v2, v2, v2
	ds_write_b16 v66, v2 offset:35840
	v_cvt_pk_bf16_f32 v2, -v3, -v3
	ds_write_b16 v66, v2 offset:36112
	v_cvt_pk_bf16_f32 v2, -v4, -v4
	ds_write_b16 v66, v2 offset:36384
	v_cvt_pk_bf16_f32 v2, -v5, -v5
	ds_write_b16 v66, v2 offset:36656
	v_cvt_pk_bf16_f32 v2, -v6, -v6
	ds_write_b16 v66, v2 offset:38016
	v_cvt_pk_bf16_f32 v2, -v7, -v7
	ds_write_b16 v66, v2 offset:38288
	v_cvt_pk_bf16_f32 v2, -v8, -v8
	ds_write_b16 v66, v2 offset:38560
	v_cvt_pk_bf16_f32 v2, -v9, -v9
	ds_write_b16 v66, v2 offset:38832
	v_cvt_pk_bf16_f32 v2, -v10, -v10
	ds_write_b16 v66, v2 offset:40192
	v_cvt_pk_bf16_f32 v2, -v11, -v11
	ds_write_b16 v66, v2 offset:40464
	v_cvt_pk_bf16_f32 v2, -v12, -v12
	ds_write_b16 v66, v2 offset:40736
	v_cvt_pk_bf16_f32 v2, -v13, -v13
	ds_write_b16 v66, v2 offset:41008
	v_cvt_pk_bf16_f32 v2, -v14, -v14
	ds_write_b16 v66, v2 offset:42368
	v_cvt_pk_bf16_f32 v2, -v15, -v15
	ds_write_b16 v66, v2 offset:42640
	v_cvt_pk_bf16_f32 v2, -v16, -v16
	ds_write_b16 v66, v2 offset:42912
	v_cvt_pk_bf16_f32 v2, -v17, -v17
	ds_write_b16 v66, v2 offset:43184
	v_cvt_pk_bf16_f32 v2, -v18, -v18
	ds_write_b16 v66, v2 offset:44544
	v_cvt_pk_bf16_f32 v2, -v19, -v19
	ds_write_b16 v66, v2 offset:44816
	v_cvt_pk_bf16_f32 v2, -v20, -v20
	ds_write_b16 v66, v2 offset:45088
	v_cvt_pk_bf16_f32 v2, -v21, -v21
	ds_write_b16 v66, v2 offset:45360
	v_cvt_pk_bf16_f32 v2, -v22, -v22
	ds_write_b16 v66, v2 offset:46720
	v_cvt_pk_bf16_f32 v2, -v23, -v23
	ds_write_b16 v66, v2 offset:46992
	v_cvt_pk_bf16_f32 v2, -v24, -v24
	ds_write_b16 v66, v2 offset:47264
	v_cvt_pk_bf16_f32 v2, -v25, -v25
	ds_write_b16 v66, v2 offset:47536
	v_cvt_pk_bf16_f32 v2, -v26, -v26
	ds_write_b16 v66, v2 offset:48896
	v_cvt_pk_bf16_f32 v2, -v27, -v27
	ds_write_b16 v66, v2 offset:49168
	v_cvt_pk_bf16_f32 v2, -v28, -v28
	ds_write_b16 v66, v2 offset:49440
	v_cvt_pk_bf16_f32 v2, -v29, -v29
	ds_write_b16 v66, v2 offset:49712
	v_cvt_pk_bf16_f32 v2, -v30, -v30
	ds_write_b16 v66, v2 offset:51072
	v_cvt_pk_bf16_f32 v2, -v31, -v31
	ds_write_b16 v66, v2 offset:51344
	v_cvt_pk_bf16_f32 v2, -v32, -v32
	ds_write_b16 v66, v2 offset:51616
	v_cvt_pk_bf16_f32 v2, -v33, -v33
	ds_write_b16 v66, v2 offset:51888
	v_cvt_pk_bf16_f32 v2, -v50, -v50
	ds_write_b16 v66, v2 offset:35904
	v_cvt_pk_bf16_f32 v2, -v51, -v51
	ds_write_b16 v66, v2 offset:36176
	v_cvt_pk_bf16_f32 v2, -v52, -v52
	ds_write_b16 v66, v2 offset:36448
	v_cvt_pk_bf16_f32 v2, -v53, -v53
	ds_write_b16 v66, v2 offset:36720
	v_cvt_pk_bf16_f32 v2, -v54, -v54
	ds_write_b16 v66, v2 offset:38080
	v_cvt_pk_bf16_f32 v2, -v55, -v55
	ds_write_b16 v66, v2 offset:38352
	v_cvt_pk_bf16_f32 v2, -v56, -v56
	ds_write_b16 v66, v2 offset:38624
	v_cvt_pk_bf16_f32 v2, -v57, -v57
	ds_write_b16 v66, v2 offset:38896
	v_cvt_pk_bf16_f32 v2, -v58, -v58
	ds_write_b16 v66, v2 offset:40256
	v_cvt_pk_bf16_f32 v2, -v59, -v59
	ds_write_b16 v66, v2 offset:40528
	v_cvt_pk_bf16_f32 v2, -v60, -v60
	ds_write_b16 v66, v2 offset:40800
	v_cvt_pk_bf16_f32 v2, -v61, -v61
	ds_write_b16 v66, v2 offset:41072
	v_cvt_pk_bf16_f32 v2, -v62, -v62
	ds_write_b16 v66, v2 offset:42432
	v_cvt_pk_bf16_f32 v2, -v63, -v63
	ds_write_b16 v66, v2 offset:42704
	v_cvt_pk_bf16_f32 v2, -v64, -v64
	ds_write_b16 v66, v2 offset:42976
	v_cvt_pk_bf16_f32 v2, -v65, -v65
	ds_write_b16 v66, v2 offset:43248
	v_cvt_pk_bf16_f32 v2, -v34, -v34
	ds_write_b16 v66, v2 offset:44608
	v_cvt_pk_bf16_f32 v2, -v35, -v35
	ds_write_b16 v66, v2 offset:44880
	v_cvt_pk_bf16_f32 v2, -v36, -v36
	ds_write_b16 v66, v2 offset:45152
	v_cvt_pk_bf16_f32 v2, -v37, -v37
	ds_write_b16 v66, v2 offset:45424
	v_cvt_pk_bf16_f32 v2, -v38, -v38
	ds_write_b16 v66, v2 offset:46784
	v_cvt_pk_bf16_f32 v2, -v39, -v39
	ds_write_b16 v66, v2 offset:47056
	v_cvt_pk_bf16_f32 v2, -v40, -v40
	ds_write_b16 v66, v2 offset:47328
	v_cvt_pk_bf16_f32 v2, -v41, -v41
	ds_write_b16 v66, v2 offset:47600
	v_cvt_pk_bf16_f32 v2, -v42, -v42
	ds_write_b16 v66, v2 offset:48960
	v_cvt_pk_bf16_f32 v2, -v43, -v43
	ds_write_b16 v66, v2 offset:49232
	v_cvt_pk_bf16_f32 v2, -v44, -v44
	ds_write_b16 v66, v2 offset:49504
	v_cvt_pk_bf16_f32 v2, -v45, -v45
	ds_write_b16 v66, v2 offset:49776
	v_cvt_pk_bf16_f32 v2, -v46, -v46
	ds_write_b16 v66, v2 offset:51136
	v_cvt_pk_bf16_f32 v2, -v47, -v47
	ds_write_b16 v66, v2 offset:51408
	v_cvt_pk_bf16_f32 v2, -v48, -v48
	ds_write_b16 v66, v2 offset:51680
	v_cvt_pk_bf16_f32 v2, -v49, -v49
	ds_write_b16 v66, v2 offset:51952
	s_branch .LBB0_313
